# 8-phase GEMMs: one static priority raise for the trailing wave half instead of per-MFMA-block priority toggling
# speedup vs baseline: 1.0130x; 1.0064x over previous
.LBB0_147:
	s_or_b64 exec, exec, s[4:5]
	s_bitcmp1_b32 s95, 0
	s_cselect_b32 s0, 0x15a0000, 0
	v_writelane_b32 v255, s0, 1
	v_readlane_b32 s4, v254, 5
	v_readlane_b32 s0, v254, 7
	v_readlane_b32 s5, v254, 6
	v_mov_b32_e32 v8, v226
	v_readlane_b32 s1, v254, 8
	s_waitcnt lgkmcnt(0)
	s_barrier
	s_and_b64 vcc, exec, s[0:1]
	v_readfirstlane_b32 s22, v8
	s_cbranch_vccz .LBB0_159
	v_lshlrev_b32_e32 v0, 4, v8
	v_add_u32_e32 v1, 0x2000, v0
	v_ashrrev_i32_e32 v2, 31, v1
	v_lshrrev_b32_e32 v2, 22, v2
	v_add_u32_e32 v2, v1, v2
	v_ashrrev_i32_e32 v9, 10, v2
	v_mul_i32_i24_e32 v2, 0x400, v9
	v_sub_u32_e32 v1, v1, v2
	s_load_dwordx2 s[4:5], s[4:5], 0xc0
	v_lshrrev_b32_e32 v2, 4, v1
	v_bitop3_b32 v1, v2, v1, 32 bitop3:0x6c
	v_ashrrev_i32_e32 v2, 31, v1
	v_lshrrev_b32_e32 v2, 26, v2
	v_add_u32_e32 v2, v1, v2
	v_lshlrev_b32_e32 v3, 3, v9
	s_waitcnt lgkmcnt(0)
	s_add_u32 s23, s4, 0x16bf0000
	v_ashrrev_i32_e32 v10, 6, v2
	v_and_b32_e32 v3, -16, v3
	s_addc_u32 s24, s5, 0
	v_readlane_b32 s0, v255, 1
	v_add_u32_e32 v3, v10, v3
	s_add_u32 s25, s4, s0
	v_and_b32_e32 v4, 3, v10
	s_mov_b32 s0, 0x1fffe0
	v_lshrrev_b32_e32 v5, 2, v3
	v_lshlrev_b32_e32 v6, 1, v3
	v_and_b32_e32 v2, 0xc0, v2
	v_and_or_b32 v4, v3, s0, v4
	v_and_b32_e32 v5, 4, v5
	v_and_b32_e32 v6, 24, v6
	v_sub_u32_e32 v1, v1, v2
	v_or3_b32 v4, v4, v5, v6
	v_lshlrev_b32_e32 v5, 5, v9
	v_ashrrev_i16_sdwa v1, v230, sext(v1) dst_sel:DWORD dst_unused:UNUSED_PAD src0_sel:DWORD src1_sel:BYTE_0
	v_and_b32_e32 v5, 32, v5
	v_bfe_i32 v11, v1, 0, 16
	v_add_lshl_u32 v1, v5, v11, 1
	v_lshl_add_u32 v128, v4, 11, v1
	v_lshl_add_u32 v130, v3, 11, v1
	v_bfe_i32 v1, v8, 27, 1
	v_lshrrev_b32_e32 v1, 22, v1
	v_add_u32_e32 v1, v0, v1
	v_and_b32_e32 v1, 0xfffffc00, v1
	v_sub_u32_e32 v0, v0, v1
	v_lshrrev_b32_e32 v1, 4, v0
	v_bitop3_b32 v1, v1, v0, 32 bitop3:0x6c
	v_ashrrev_i32_e32 v0, 31, v0
	v_lshrrev_b32_e32 v0, 26, v0
	v_add_u32_e32 v0, v1, v0
	v_ashrrev_i32_e32 v12, 6, v0
	v_ashrrev_i32_e32 v0, 31, v8
	v_lshrrev_b32_e32 v0, 26, v0
	v_add_u32_e32 v0, v8, v0
	v_ashrrev_i32_e32 v13, 6, v0
	v_lshlrev_b32_e32 v0, 3, v13
	v_and_b32_e32 v0, -16, v0
	v_add_u32_e32 v0, v12, v0
	v_and_b32_e32 v2, 3, v12
	v_lshrrev_b32_e32 v3, 2, v0
	v_lshlrev_b32_e32 v4, 1, v0
	v_and_or_b32 v2, v0, s0, v2
	v_and_b32_e32 v3, 4, v3
	v_and_b32_e32 v4, 24, v4
	v_or3_b32 v2, v2, v3, v4
	v_mul_i32_i24_e32 v4, 64, v12
	s_addc_u32 s26, s5, 0
	s_ashr_i32 s9, s22, 6
	v_sub_u32_e32 v1, v1, v4
	s_ashr_i32 s8, s22, 8
	s_lshl_b32 s27, s9, 10
	v_lshlrev_b32_e32 v3, 5, v13
	v_ashrrev_i16_sdwa v1, v230, sext(v1) dst_sel:DWORD dst_unused:UNUSED_PAD src0_sel:DWORD src1_sel:BYTE_0
	v_readlane_b32 s0, v254, 14
	v_and_b32_e32 v3, 32, v3
	v_bfe_i32 v14, v1, 0, 16
	v_readlane_b32 s1, v254, 15
	s_add_u32 s18, s25, s0
	v_add_lshl_u32 v1, v3, v14, 1
	s_addc_u32 s19, s26, s1
	s_add_i32 s28, s27, 0
	v_lshl_add_u32 v144, v2, 11, v1
	s_add_i32 m0, s28, 0x10000
	v_readlane_b32 s0, v254, 12
	global_load_lds_dwordx4 v144, s[18:19]
	s_add_i32 m0, s28, 0x12000
	v_readlane_b32 s1, v254, 13
	s_add_u32 s16, s23, s0
	v_lshl_add_u32 v132, v0, 11, v1
	global_load_lds_dwordx4 v128, s[18:19]
	s_addc_u32 s17, s24, s1
	s_mov_b32 m0, s28
	s_add_i32 s29, s28, 0x2000
	global_load_lds_dwordx4 v132, s[16:17]
	s_mov_b32 m0, s29
	s_add_u32 s6, s18, 0x40000
	global_load_lds_dwordx4 v130, s[16:17]
	s_addc_u32 s7, s19, 0
	s_add_i32 m0, s28, 0x14000
	v_mov_b32_e32 v129, v145
	global_load_lds_dwordx4 v144, s[6:7]
	s_add_i32 m0, s28, 0x16000
	v_mov_b32_e32 v133, v145
	global_load_lds_dwordx4 v128, s[6:7]
	s_add_u32 s6, s16, 0x40000
	s_addc_u32 s7, s17, 0
	s_add_i32 s30, s28, 0x4000
	s_mov_b32 m0, s30
	s_add_i32 s31, s28, 0x6000
	global_load_lds_dwordx4 v132, s[6:7]
	s_mov_b32 m0, s31
	v_mov_b32_e32 v131, v145
	global_load_lds_dwordx4 v130, s[6:7]
	v_lshl_add_u64 v[6:7], s[18:19], 0, v[144:145]
	v_lshl_add_u64 v[4:5], s[18:19], 0, v[128:129]
	v_lshl_add_u64 v[2:3], s[16:17], 0, v[132:133]
	s_cmp_lg_u32 s8, 1
	v_lshl_add_u64 v[0:1], s[16:17], 0, v[130:131]
	s_cbranch_scc1 .LBB0_150
	s_setprio 1
	s_barrier

.LBB0_154:
	s_add_u32 s0, s16, 0xfffc0080
	s_addc_u32 s1, s17, -1
	s_add_i32 s33, 0, 0x10000
	v_add_u32_e32 v153, s33, v143
	ds_read_b128 v[138:141], v153
	ds_read_b128 v[154:157], v153 offset:1024
	ds_read_b128 v[158:161], v153 offset:2048
	ds_read_b128 v[162:165], v153 offset:3072
	s_cmp_eq_u32 s55, 12
	s_cselect_b32 s21, s11, s1
	s_cselect_b32 s20, s45, s0
	s_cselect_b32 s19, s9, s54
	s_cselect_b32 s18, s48, s49
	v_lshl_add_u64 v[198:199], s[16:17], 0, v[134:135]
	s_add_i32 m0, s28, 0xc000
	ds_read_b128 v[166:169], v152
	ds_read_b128 v[170:173], v152 offset:1024
	ds_read_b128 v[174:177], v152 offset:2048
	ds_read_b128 v[178:181], v152 offset:3072
	ds_read_b128 v[182:185], v152 offset:4096
	ds_read_b128 v[186:189], v152 offset:5120
	ds_read_b128 v[190:193], v152 offset:6144
	ds_read_b128 v[194:197], v152 offset:7168
	global_load_lds_dwordx4 v[198:199], off
	v_lshl_add_u64 v[198:199], s[16:17], 0, v[136:137]
	s_add_i32 m0, s28, 0xe000
	s_nop 0
	global_load_lds_dwordx4 v[198:199], off
	s_waitcnt lgkmcnt(8)
	s_barrier
	s_waitcnt lgkmcnt(0)

	s_waitcnt lgkmcnt(0)
	v_mfma_f32_16x16x32_bf16 v[124:127], v[138:141], v[166:169], v[124:127]
	v_mfma_f32_16x16x32_bf16 v[120:123], v[158:161], v[166:169], v[120:123]
	v_mfma_f32_16x16x32_bf16 v[116:119], v[138:141], v[174:177], v[116:119]
	v_mfma_f32_16x16x32_bf16 v[108:111], v[158:161], v[174:177], v[108:111]
	v_mfma_f32_16x16x32_bf16 v[100:103], v[138:141], v[182:185], v[100:103]
	v_mfma_f32_16x16x32_bf16 v[92:95], v[158:161], v[182:185], v[92:95]
	v_mfma_f32_16x16x32_bf16 v[84:87], v[138:141], v[190:193], v[84:87]
	v_mfma_f32_16x16x32_bf16 v[76:79], v[158:161], v[190:193], v[76:79]
	v_mfma_f32_16x16x32_bf16 v[124:127], v[154:157], v[170:173], v[124:127]
	v_mfma_f32_16x16x32_bf16 v[120:123], v[162:165], v[170:173], v[120:123]
	v_mfma_f32_16x16x32_bf16 v[116:119], v[154:157], v[178:181], v[116:119]
	v_mfma_f32_16x16x32_bf16 v[108:111], v[162:165], v[178:181], v[108:111]
	v_mfma_f32_16x16x32_bf16 v[100:103], v[154:157], v[186:189], v[100:103]
	v_mfma_f32_16x16x32_bf16 v[92:95], v[162:165], v[186:189], v[92:95]
	v_mfma_f32_16x16x32_bf16 v[84:87], v[154:157], v[194:197], v[84:87]
	v_mfma_f32_16x16x32_bf16 v[76:79], v[162:165], v[194:197], v[76:79]

	s_barrier
	s_add_i32 s0, 0, 0x14000
	s_add_i32 s1, s33, s27
	v_add_u32_e32 v153, s0, v143
	v_lshl_add_u64 v[214:215], s[18:19], 0, v[144:145]
	s_mov_b32 m0, s1
	ds_read_b128 v[198:201], v153
	ds_read_b128 v[202:205], v153 offset:1024
	ds_read_b128 v[206:209], v153 offset:2048
	ds_read_b128 v[210:213], v153 offset:3072
	global_load_lds_dwordx4 v[214:215], off
	v_lshl_add_u64 v[216:217], s[18:19], 0, v[128:129]
	s_add_i32 m0, s1, 0x2000
	s_nop 0
	global_load_lds_dwordx4 v[216:217], off
	s_barrier
	s_waitcnt lgkmcnt(0)

	s_waitcnt lgkmcnt(0)
	v_mfma_f32_16x16x32_bf16 v[112:115], v[198:201], v[166:169], v[112:115]
	v_mfma_f32_16x16x32_bf16 v[104:107], v[206:209], v[166:169], v[104:107]
	v_mfma_f32_16x16x32_bf16 v[96:99], v[198:201], v[174:177], v[96:99]
	v_mfma_f32_16x16x32_bf16 v[88:91], v[206:209], v[174:177], v[88:91]
	v_mfma_f32_16x16x32_bf16 v[80:83], v[198:201], v[182:185], v[80:83]
	v_mfma_f32_16x16x32_bf16 v[72:75], v[206:209], v[182:185], v[72:75]
	v_mfma_f32_16x16x32_bf16 v[68:71], v[198:201], v[190:193], v[68:71]
	v_mfma_f32_16x16x32_bf16 v[64:67], v[206:209], v[190:193], v[64:67]
	v_mfma_f32_16x16x32_bf16 v[112:115], v[202:205], v[170:173], v[112:115]
	v_mfma_f32_16x16x32_bf16 v[104:107], v[210:213], v[170:173], v[104:107]
	v_mfma_f32_16x16x32_bf16 v[96:99], v[202:205], v[178:181], v[96:99]
	v_mfma_f32_16x16x32_bf16 v[88:91], v[210:213], v[178:181], v[88:91]
	v_mfma_f32_16x16x32_bf16 v[80:83], v[202:205], v[186:189], v[80:83]
	v_mfma_f32_16x16x32_bf16 v[72:75], v[210:213], v[186:189], v[72:75]
	v_mfma_f32_16x16x32_bf16 v[68:71], v[202:205], v[194:197], v[68:71]
	v_mfma_f32_16x16x32_bf16 v[64:67], v[210:213], v[194:197], v[64:67]

	s_mov_b32 m0, s28
	v_lshl_add_u64 v[218:219], s[20:21], 0, v[132:133]
	s_barrier
	ds_read_b128 v[166:169], v152 offset:16384
	ds_read_b128 v[170:173], v152 offset:17408
	ds_read_b128 v[174:177], v152 offset:18432
	ds_read_b128 v[178:181], v152 offset:19456
	ds_read_b128 v[182:185], v152 offset:20480
	ds_read_b128 v[186:189], v152 offset:21504
	ds_read_b128 v[190:193], v152 offset:22528
	ds_read_b128 v[194:197], v152 offset:23552
	global_load_lds_dwordx4 v[218:219], off
	v_lshl_add_u64 v[220:221], s[20:21], 0, v[130:131]
	s_mov_b32 m0, s29
	s_nop 0
	global_load_lds_dwordx4 v[220:221], off
	s_barrier
	s_waitcnt lgkmcnt(0)

	s_waitcnt lgkmcnt(0)
	v_mfma_f32_16x16x32_bf16 v[60:63], v[138:141], v[166:169], v[60:63]
	v_mfma_f32_16x16x32_bf16 v[56:59], v[158:161], v[166:169], v[56:59]
	v_mfma_f32_16x16x32_bf16 v[52:55], v[138:141], v[174:177], v[52:55]
	v_mfma_f32_16x16x32_bf16 v[44:47], v[158:161], v[174:177], v[44:47]
	v_mfma_f32_16x16x32_bf16 v[36:39], v[138:141], v[182:185], v[36:39]
	v_mfma_f32_16x16x32_bf16 v[28:31], v[158:161], v[182:185], v[28:31]
	v_mfma_f32_16x16x32_bf16 v[20:23], v[138:141], v[190:193], v[20:23]
	v_mfma_f32_16x16x32_bf16 v[12:15], v[158:161], v[190:193], v[12:15]
	v_mfma_f32_16x16x32_bf16 v[60:63], v[154:157], v[170:173], v[60:63]
	v_mfma_f32_16x16x32_bf16 v[56:59], v[162:165], v[170:173], v[56:59]
	v_mfma_f32_16x16x32_bf16 v[52:55], v[154:157], v[178:181], v[52:55]
	v_mfma_f32_16x16x32_bf16 v[44:47], v[162:165], v[178:181], v[44:47]
	v_mfma_f32_16x16x32_bf16 v[36:39], v[154:157], v[186:189], v[36:39]
	v_mfma_f32_16x16x32_bf16 v[28:31], v[162:165], v[186:189], v[28:31]
	v_mfma_f32_16x16x32_bf16 v[20:23], v[154:157], v[194:197], v[20:23]
	v_mfma_f32_16x16x32_bf16 v[12:15], v[162:165], v[194:197], v[12:15]

	s_barrier
	s_add_u32 s56, s18, 0x40000
	s_addc_u32 s57, s19, 0
	s_add_i32 s0, s0, s27
	v_lshl_add_u64 v[138:139], s[56:57], 0, v[144:145]
	s_mov_b32 m0, s0
	s_nop 0
	global_load_lds_dwordx4 v[138:139], off
	v_lshl_add_u64 v[138:139], s[56:57], 0, v[128:129]
	s_add_i32 m0, s0, 0x2000
	s_nop 0
	global_load_lds_dwordx4 v[138:139], off
	s_waitcnt vmcnt(6)
	s_barrier

	v_mfma_f32_16x16x32_bf16 v[48:51], v[198:201], v[166:169], v[48:51]
	v_mfma_f32_16x16x32_bf16 v[40:43], v[206:209], v[166:169], v[40:43]
	v_mfma_f32_16x16x32_bf16 v[32:35], v[198:201], v[174:177], v[32:35]
	v_mfma_f32_16x16x32_bf16 v[24:27], v[206:209], v[174:177], v[24:27]
	v_mfma_f32_16x16x32_bf16 v[16:19], v[198:201], v[182:185], v[16:19]
	v_mfma_f32_16x16x32_bf16 v[8:11], v[206:209], v[182:185], v[8:11]
	v_mfma_f32_16x16x32_bf16 v[4:7], v[198:201], v[190:193], v[4:7]
	v_mfma_f32_16x16x32_bf16 v[0:3], v[206:209], v[190:193], v[0:3]
	v_mfma_f32_16x16x32_bf16 v[48:51], v[202:205], v[170:173], v[48:51]
	v_mfma_f32_16x16x32_bf16 v[40:43], v[210:213], v[170:173], v[40:43]
	v_mfma_f32_16x16x32_bf16 v[32:35], v[202:205], v[178:181], v[32:35]
	v_mfma_f32_16x16x32_bf16 v[24:27], v[210:213], v[178:181], v[24:27]
	v_mfma_f32_16x16x32_bf16 v[16:19], v[202:205], v[186:189], v[16:19]
	v_mfma_f32_16x16x32_bf16 v[8:11], v[210:213], v[186:189], v[8:11]
	v_mfma_f32_16x16x32_bf16 v[4:7], v[202:205], v[194:197], v[4:7]
	v_mfma_f32_16x16x32_bf16 v[0:3], v[210:213], v[194:197], v[0:3]

	s_add_i32 s0, 0, 0x18000
	v_add_u32_e32 v153, s0, v143
	s_barrier
	ds_read_b128 v[138:141], v153
	ds_read_b128 v[154:157], v153 offset:1024
	ds_read_b128 v[158:161], v153 offset:2048
	ds_read_b128 v[162:165], v153 offset:3072
	s_add_u32 s20, s20, 0x40000
	s_addc_u32 s21, s21, 0
	s_mov_b32 m0, s30
	v_lshl_add_u64 v[198:199], s[20:21], 0, v[132:133]
	ds_read_b128 v[166:169], v152 offset:32768
	ds_read_b128 v[170:173], v152 offset:33792
	ds_read_b128 v[174:177], v152 offset:34816
	ds_read_b128 v[178:181], v152 offset:35840
	ds_read_b128 v[182:185], v152 offset:36864
	ds_read_b128 v[186:189], v152 offset:37888
	ds_read_b128 v[190:193], v152 offset:38912
	ds_read_b128 v[194:197], v152 offset:39936
	global_load_lds_dwordx4 v[198:199], off
	v_lshl_add_u64 v[198:199], s[20:21], 0, v[130:131]
	s_mov_b32 m0, s31
	s_nop 0
	global_load_lds_dwordx4 v[198:199], off
	s_waitcnt lgkmcnt(8)
	s_barrier
	s_waitcnt lgkmcnt(0)

	s_waitcnt lgkmcnt(0)
	v_mfma_f32_16x16x32_bf16 v[124:127], v[138:141], v[166:169], v[124:127]
	v_mfma_f32_16x16x32_bf16 v[120:123], v[158:161], v[166:169], v[120:123]
	v_mfma_f32_16x16x32_bf16 v[116:119], v[138:141], v[174:177], v[116:119]
	v_mfma_f32_16x16x32_bf16 v[108:111], v[158:161], v[174:177], v[108:111]
	v_mfma_f32_16x16x32_bf16 v[100:103], v[138:141], v[182:185], v[100:103]
	v_mfma_f32_16x16x32_bf16 v[92:95], v[158:161], v[182:185], v[92:95]
	v_mfma_f32_16x16x32_bf16 v[84:87], v[138:141], v[190:193], v[84:87]
	v_mfma_f32_16x16x32_bf16 v[76:79], v[158:161], v[190:193], v[76:79]
	v_mfma_f32_16x16x32_bf16 v[124:127], v[154:157], v[170:173], v[124:127]
	v_mfma_f32_16x16x32_bf16 v[120:123], v[162:165], v[170:173], v[120:123]
	v_mfma_f32_16x16x32_bf16 v[116:119], v[154:157], v[178:181], v[116:119]
	v_mfma_f32_16x16x32_bf16 v[108:111], v[162:165], v[178:181], v[108:111]
	v_mfma_f32_16x16x32_bf16 v[100:103], v[154:157], v[186:189], v[100:103]
	v_mfma_f32_16x16x32_bf16 v[92:95], v[162:165], v[186:189], v[92:95]
	v_mfma_f32_16x16x32_bf16 v[84:87], v[154:157], v[194:197], v[84:87]
	v_mfma_f32_16x16x32_bf16 v[76:79], v[162:165], v[194:197], v[76:79]

	s_barrier
	s_add_i32 s1, 0, 0x1c000
	s_add_i32 s0, s0, s27
	v_add_u32_e32 v153, s1, v143
	v_lshl_add_u64 v[214:215], v[214:215], 0, s[86:87]
	s_mov_b32 m0, s0
	ds_read_b128 v[198:201], v153
	ds_read_b128 v[202:205], v153 offset:1024
	ds_read_b128 v[206:209], v153 offset:2048
	ds_read_b128 v[210:213], v153 offset:3072
	global_load_lds_dwordx4 v[214:215], off
	v_lshl_add_u64 v[214:215], v[216:217], 0, s[86:87]
	s_add_i32 m0, s0, 0x2000
	s_nop 0
	global_load_lds_dwordx4 v[214:215], off
	s_barrier
	s_waitcnt lgkmcnt(0)

	s_waitcnt lgkmcnt(0)
	v_mfma_f32_16x16x32_bf16 v[112:115], v[198:201], v[166:169], v[112:115]
	v_mfma_f32_16x16x32_bf16 v[104:107], v[206:209], v[166:169], v[104:107]
	v_mfma_f32_16x16x32_bf16 v[96:99], v[198:201], v[174:177], v[96:99]
	v_mfma_f32_16x16x32_bf16 v[88:91], v[206:209], v[174:177], v[88:91]
	v_mfma_f32_16x16x32_bf16 v[80:83], v[198:201], v[182:185], v[80:83]
	v_mfma_f32_16x16x32_bf16 v[72:75], v[206:209], v[182:185], v[72:75]
	v_mfma_f32_16x16x32_bf16 v[68:71], v[198:201], v[190:193], v[68:71]
	v_mfma_f32_16x16x32_bf16 v[64:67], v[206:209], v[190:193], v[64:67]
	v_mfma_f32_16x16x32_bf16 v[112:115], v[202:205], v[170:173], v[112:115]
	v_mfma_f32_16x16x32_bf16 v[104:107], v[210:213], v[170:173], v[104:107]
	v_mfma_f32_16x16x32_bf16 v[96:99], v[202:205], v[178:181], v[96:99]
	v_mfma_f32_16x16x32_bf16 v[88:91], v[210:213], v[178:181], v[88:91]
	v_mfma_f32_16x16x32_bf16 v[80:83], v[202:205], v[186:189], v[80:83]
	v_mfma_f32_16x16x32_bf16 v[72:75], v[210:213], v[186:189], v[72:75]
	v_mfma_f32_16x16x32_bf16 v[68:71], v[202:205], v[194:197], v[68:71]
	v_mfma_f32_16x16x32_bf16 v[64:67], v[210:213], v[194:197], v[64:67]

	s_mov_b32 m0, s34
	v_lshl_add_u64 v[214:215], v[218:219], 0, s[86:87]
	s_barrier
	ds_read_b128 v[166:169], v152 offset:49152
	ds_read_b128 v[170:173], v152 offset:50176
	ds_read_b128 v[174:177], v152 offset:51200
	ds_read_b128 v[178:181], v152 offset:52224
	ds_read_b128 v[182:185], v152 offset:53248
	ds_read_b128 v[186:189], v152 offset:54272
	ds_read_b128 v[190:193], v152 offset:55296
	ds_read_b128 v[194:197], v152 offset:56320
	global_load_lds_dwordx4 v[214:215], off
	v_lshl_add_u64 v[214:215], v[220:221], 0, s[86:87]
	s_mov_b32 m0, s35
	s_nop 0
	global_load_lds_dwordx4 v[214:215], off
	s_barrier
	s_waitcnt lgkmcnt(0)

	s_waitcnt lgkmcnt(0)
	v_mfma_f32_16x16x32_bf16 v[60:63], v[138:141], v[166:169], v[60:63]
	v_mfma_f32_16x16x32_bf16 v[56:59], v[158:161], v[166:169], v[56:59]
	v_mfma_f32_16x16x32_bf16 v[52:55], v[138:141], v[174:177], v[52:55]
	v_mfma_f32_16x16x32_bf16 v[44:47], v[158:161], v[174:177], v[44:47]
	v_mfma_f32_16x16x32_bf16 v[36:39], v[138:141], v[182:185], v[36:39]
	v_mfma_f32_16x16x32_bf16 v[28:31], v[158:161], v[182:185], v[28:31]
	v_mfma_f32_16x16x32_bf16 v[20:23], v[138:141], v[190:193], v[20:23]
	v_mfma_f32_16x16x32_bf16 v[12:15], v[158:161], v[190:193], v[12:15]
	v_mfma_f32_16x16x32_bf16 v[60:63], v[154:157], v[170:173], v[60:63]
	v_mfma_f32_16x16x32_bf16 v[56:59], v[162:165], v[170:173], v[56:59]
	v_mfma_f32_16x16x32_bf16 v[52:55], v[154:157], v[178:181], v[52:55]
	v_mfma_f32_16x16x32_bf16 v[44:47], v[162:165], v[178:181], v[44:47]
	v_mfma_f32_16x16x32_bf16 v[36:39], v[154:157], v[186:189], v[36:39]
	v_mfma_f32_16x16x32_bf16 v[28:31], v[162:165], v[186:189], v[28:31]
	v_mfma_f32_16x16x32_bf16 v[20:23], v[154:157], v[194:197], v[20:23]
	v_mfma_f32_16x16x32_bf16 v[12:15], v[162:165], v[194:197], v[12:15]

	s_barrier
	s_add_u32 s18, s18, 0x40080
	s_addc_u32 s19, s19, 0
	s_add_i32 s0, s1, s27
	v_lshl_add_u64 v[138:139], s[18:19], 0, v[144:145]
	s_mov_b32 m0, s0
	s_nop 0
	global_load_lds_dwordx4 v[138:139], off
	v_lshl_add_u64 v[138:139], s[18:19], 0, v[128:129]
	s_add_i32 m0, s0, 0x2000
	s_nop 0
	global_load_lds_dwordx4 v[138:139], off
	s_waitcnt vmcnt(6)
	s_barrier

	v_mfma_f32_16x16x32_bf16 v[48:51], v[198:201], v[166:169], v[48:51]
	v_mfma_f32_16x16x32_bf16 v[40:43], v[206:209], v[166:169], v[40:43]
	v_mfma_f32_16x16x32_bf16 v[32:35], v[198:201], v[174:177], v[32:35]
	v_mfma_f32_16x16x32_bf16 v[24:27], v[206:209], v[174:177], v[24:27]
	v_mfma_f32_16x16x32_bf16 v[16:19], v[198:201], v[182:185], v[16:19]
	v_mfma_f32_16x16x32_bf16 v[8:11], v[206:209], v[182:185], v[8:11]
	v_mfma_f32_16x16x32_bf16 v[4:7], v[198:201], v[190:193], v[4:7]
	v_mfma_f32_16x16x32_bf16 v[0:3], v[206:209], v[190:193], v[0:3]
	v_mfma_f32_16x16x32_bf16 v[48:51], v[202:205], v[170:173], v[48:51]
	v_mfma_f32_16x16x32_bf16 v[40:43], v[210:213], v[170:173], v[40:43]
	v_mfma_f32_16x16x32_bf16 v[32:35], v[202:205], v[178:181], v[32:35]
	v_mfma_f32_16x16x32_bf16 v[24:27], v[210:213], v[178:181], v[24:27]
	v_mfma_f32_16x16x32_bf16 v[16:19], v[202:205], v[186:189], v[16:19]
	v_mfma_f32_16x16x32_bf16 v[8:11], v[210:213], v[186:189], v[8:11]
	v_mfma_f32_16x16x32_bf16 v[4:7], v[202:205], v[194:197], v[4:7]
	v_mfma_f32_16x16x32_bf16 v[0:3], v[210:213], v[194:197], v[0:3]

	s_add_i32 s55, s55, 2
	s_add_u32 s16, s16, 0x100
	s_addc_u32 s17, s17, 0
	s_add_u32 s49, s49, 0x100
	s_addc_u32 s54, s54, 0
	s_cmp_gt_u32 s55, 13
	s_barrier
	s_cbranch_scc0 .LBB0_154
	v_lshl_or_b32 v140, s37, 8, v146
	v_lshl_add_u32 v153, s44, 8, v142
	v_ashrrev_i32_e32 v141, 31, v140
	v_mov_b64_e32 v[138:139], s[6:7]
	v_mad_i64_i32 v[154:155], s[16:17], v153, s62, v[138:139]
	v_lshlrev_b64 v[140:141], 1, v[140:141]
	v_lshl_add_u64 v[154:155], v[154:155], 0, v[140:141]
	v_cvt_pk_bf16_f32 v124, v124, v125
	v_cvt_pk_bf16_f32 v125, v126, v127
	v_cvt_pk_bf16_f32 v126, v120, v121
	v_cvt_pk_bf16_f32 v127, v122, v123
	global_store_dwordx4 v[154:155], v[124:127], off
	v_cvt_pk_bf16_f32 v112, v112, v113
	v_cvt_pk_bf16_f32 v113, v114, v115
	v_cvt_pk_bf16_f32 v114, v104, v105
	v_or_b32_e32 v104, 16, v153
	v_mad_i64_i32 v[104:105], s[16:17], v104, s62, v[138:139]
	v_cvt_pk_bf16_f32 v115, v106, v107
	global_store_dwordx4 v[154:155], v[112:115], off offset:256
	s_and_b64 vcc, exec, s[4:5]
	s_mov_b32 s37, s8
	v_lshl_add_u64 v[112:113], v[104:105], 0, v[140:141]
	v_cvt_pk_bf16_f32 v104, v116, v117
	v_cvt_pk_bf16_f32 v105, v118, v119
	v_cvt_pk_bf16_f32 v106, v108, v109
	v_cvt_pk_bf16_f32 v107, v110, v111
	global_store_dwordx4 v[112:113], v[104:107], off
	v_cvt_pk_bf16_f32 v96, v96, v97
	v_cvt_pk_bf16_f32 v97, v98, v99
	v_cvt_pk_bf16_f32 v98, v88, v89
	v_or_b32_e32 v88, 32, v153
	v_mad_i64_i32 v[88:89], s[16:17], v88, s62, v[138:139]
	v_cvt_pk_bf16_f32 v99, v90, v91
	global_store_dwordx4 v[112:113], v[96:99], off offset:256
	s_mov_b32 s44, s10
	s_mov_b64 s[18:19], s[14:15]
	v_lshl_add_u64 v[96:97], v[88:89], 0, v[140:141]
	v_cvt_pk_bf16_f32 v88, v100, v101
	v_cvt_pk_bf16_f32 v89, v102, v103
	v_cvt_pk_bf16_f32 v90, v92, v93
	v_cvt_pk_bf16_f32 v91, v94, v95
	global_store_dwordx4 v[96:97], v[88:91], off
	v_cvt_pk_bf16_f32 v80, v80, v81
	v_cvt_pk_bf16_f32 v81, v82, v83
	v_cvt_pk_bf16_f32 v82, v72, v73
	v_or_b32_e32 v72, 48, v153
	v_mad_i64_i32 v[72:73], s[16:17], v72, s62, v[138:139]
	v_cvt_pk_bf16_f32 v83, v74, v75
	global_store_dwordx4 v[96:97], v[80:83], off offset:256
	s_nop 1
	v_lshl_add_u64 v[80:81], v[72:73], 0, v[140:141]
	v_cvt_pk_bf16_f32 v72, v84, v85
	v_cvt_pk_bf16_f32 v73, v86, v87
	v_cvt_pk_bf16_f32 v74, v76, v77
	v_cvt_pk_bf16_f32 v75, v78, v79
	global_store_dwordx4 v[80:81], v[72:75], off
	v_cvt_pk_bf16_f32 v68, v68, v69
	v_cvt_pk_bf16_f32 v69, v70, v71
	v_cvt_pk_bf16_f32 v70, v64, v65
	v_add_u32_e32 v64, 0x80, v153
	v_mad_i64_i32 v[64:65], s[16:17], v64, s62, v[138:139]
	v_lshl_add_u64 v[64:65], v[64:65], 0, v[140:141]
	v_cvt_pk_bf16_f32 v71, v66, v67
	global_store_dwordx4 v[80:81], v[68:71], off offset:256
	v_cvt_pk_bf16_f32 v60, v60, v61
	v_cvt_pk_bf16_f32 v61, v62, v63
	v_cvt_pk_bf16_f32 v62, v56, v57
	v_cvt_pk_bf16_f32 v63, v58, v59
	global_store_dwordx4 v[64:65], v[60:63], off
	v_cvt_pk_bf16_f32 v48, v48, v49
	v_cvt_pk_bf16_f32 v49, v50, v51
	v_cvt_pk_bf16_f32 v50, v40, v41
	v_add_u32_e32 v40, 0x90, v153
	v_mad_i64_i32 v[40:41], s[16:17], v40, s62, v[138:139]
	v_cvt_pk_bf16_f32 v51, v42, v43
	global_store_dwordx4 v[64:65], v[48:51], off offset:256
	s_nop 1
	v_lshl_add_u64 v[48:49], v[40:41], 0, v[140:141]
	v_cvt_pk_bf16_f32 v40, v52, v53
	v_cvt_pk_bf16_f32 v41, v54, v55
	v_cvt_pk_bf16_f32 v42, v44, v45
	v_cvt_pk_bf16_f32 v43, v46, v47
	global_store_dwordx4 v[48:49], v[40:43], off
	v_cvt_pk_bf16_f32 v32, v32, v33
	v_cvt_pk_bf16_f32 v33, v34, v35
	v_cvt_pk_bf16_f32 v34, v24, v25
	v_add_u32_e32 v24, 0xa0, v153
	v_mad_i64_i32 v[24:25], s[16:17], v24, s62, v[138:139]
	v_cvt_pk_bf16_f32 v35, v26, v27
	global_store_dwordx4 v[48:49], v[32:35], off offset:256
	s_nop 1
	v_lshl_add_u64 v[32:33], v[24:25], 0, v[140:141]
	v_cvt_pk_bf16_f32 v24, v36, v37
	v_cvt_pk_bf16_f32 v25, v38, v39
	v_cvt_pk_bf16_f32 v26, v28, v29
	v_cvt_pk_bf16_f32 v27, v30, v31
	global_store_dwordx4 v[32:33], v[24:27], off
	v_cvt_pk_bf16_f32 v16, v16, v17
	v_cvt_pk_bf16_f32 v17, v18, v19
	v_cvt_pk_bf16_f32 v18, v8, v9
	v_add_u32_e32 v8, 0xb0, v153
	v_mad_i64_i32 v[8:9], s[16:17], v8, s62, v[138:139]
	v_cvt_pk_bf16_f32 v19, v10, v11
	global_store_dwordx4 v[32:33], v[16:19], off offset:256
	s_mov_b64 s[16:17], s[12:13]
	s_nop 0
	v_lshl_add_u64 v[16:17], v[8:9], 0, v[140:141]
	v_cvt_pk_bf16_f32 v8, v20, v21
	v_cvt_pk_bf16_f32 v9, v22, v23
	v_cvt_pk_bf16_f32 v10, v12, v13
	v_cvt_pk_bf16_f32 v11, v14, v15
	global_store_dwordx4 v[16:17], v[8:11], off
	v_cvt_pk_bf16_f32 v4, v4, v5
	v_cvt_pk_bf16_f32 v5, v6, v7
	v_cvt_pk_bf16_f32 v6, v0, v1
	v_cvt_pk_bf16_f32 v7, v2, v3
	global_store_dwordx4 v[16:17], v[4:7], off offset:256
	s_cbranch_vccz .LBB0_151
	s_waitcnt vmcnt(0)
	s_cmpk_gt_u32 s22, 0xff
	s_cbranch_scc1 .LBB0_158
	s_barrier
.LBB0_158:
	s_setprio 0
	s_barrier

.LBB0_1025:
	s_or_b64 exec, exec, s[6:7]
	v_readlane_b32 s0, v255, 7
	s_mov_b64 s[6:7], s[70:71]
	v_mov_b32_e32 v8, v226
	v_readlane_b32 s1, v255, 8
	s_waitcnt lgkmcnt(0)
	s_barrier
	s_and_b64 vcc, exec, s[0:1]
	v_readfirstlane_b32 s24, v8
	s_cbranch_vccnz .LBB0_1041
	v_lshlrev_b32_e32 v0, 4, v8
	v_add_u32_e32 v1, 0x2000, v0
	v_ashrrev_i32_e32 v2, 31, v1
	v_lshrrev_b32_e32 v2, 22, v2
	v_add_u32_e32 v2, v1, v2
	v_ashrrev_i32_e32 v9, 10, v2
	v_mul_i32_i24_e32 v3, 0x400, v9
	v_sub_u32_e32 v1, v1, v3
	v_lshrrev_b32_e32 v3, 4, v1
	v_bitop3_b32 v1, v3, v1, 32 bitop3:0x6c
	v_ashrrev_i32_e32 v3, 31, v1
	v_lshrrev_b32_e32 v3, 26, v3
	v_add_u32_e32 v3, v1, v3
	v_ashrrev_i32_e32 v10, 6, v3
	v_and_b32_e32 v3, 0xc0, v3
	v_sub_u32_e32 v1, v1, v3
	v_lshlrev_b32_e32 v2, 5, v9
	v_ashrrev_i16_sdwa v1, v230, sext(v1) dst_sel:DWORD dst_unused:UNUSED_PAD src0_sel:DWORD src1_sel:BYTE_0
	v_and_b32_e32 v2, 32, v2
	v_bfe_i32 v11, v1, 0, 16
	v_add_u32_e32 v1, v2, v11
	v_lshlrev_b32_e32 v2, 3, v9
	v_and_b32_e32 v2, 0x1ffff0, v2
	v_add_lshl_u32 v2, v10, v2, 11
	v_lshl_add_u32 v152, v1, 1, v2
	v_bfe_i32 v2, v8, 27, 1
	v_lshrrev_b32_e32 v2, 22, v2
	v_add_u32_e32 v2, v0, v2
	s_load_dwordx4 s[8:11], s[6:7], 0xb8
	s_load_dwordx2 s[4:5], s[6:7], 0x0
	v_and_b32_e32 v2, 0xfffffc00, v2
	v_sub_u32_e32 v0, v0, v2
	v_lshrrev_b32_e32 v2, 4, v0
	v_bitop3_b32 v2, v2, v0, 32 bitop3:0x6c
	v_ashrrev_i32_e32 v0, 31, v0
	v_lshrrev_b32_e32 v0, 26, v0
	s_waitcnt lgkmcnt(0)
	s_add_u32 s25, s10, 0x1abf0000
	v_ashrrev_i32_e32 v1, 31, v8
	v_add_u32_e32 v0, v2, v0
	s_addc_u32 s26, s11, 0
	v_readlane_b32 s0, v255, 1
	v_lshrrev_b32_e32 v1, 26, v1
	v_ashrrev_i32_e32 v13, 6, v0
	s_add_u32 s0, s10, s0
	v_add_u32_e32 v1, v8, v1
	v_mul_i32_i24_e32 v0, 64, v13
	s_addc_u32 s1, s11, 0
	v_ashrrev_i32_e32 v12, 6, v1
	v_sub_u32_e32 v0, v2, v0
	s_add_u32 s27, s0, 0x1380000
	v_lshlrev_b32_e32 v1, 5, v12
	v_ashrrev_i16_sdwa v0, v230, sext(v0) dst_sel:DWORD dst_unused:UNUSED_PAD src0_sel:DWORD src1_sel:BYTE_0
	s_addc_u32 s28, s1, 0
	s_ashr_i32 s12, s24, 6
	v_and_b32_e32 v1, 32, v1
	v_bfe_i32 v14, v0, 0, 16
	s_ashr_i32 s13, s24, 8
	s_lshl_b32 s29, s12, 10
	v_add_u32_e32 v0, v1, v14
	v_lshlrev_b32_e32 v1, 3, v12
	v_readlane_b32 s0, v254, 42
	v_and_b32_e32 v1, 0x1ffff0, v1
	v_readlane_b32 s1, v254, 43
	s_add_u32 s20, s27, s0
	v_add_lshl_u32 v1, v13, v1, 11
	s_addc_u32 s21, s28, s1
	s_add_i32 s30, s29, 0
	v_lshl_add_u32 v144, v0, 1, v1
	s_add_i32 m0, s30, 0x10000
	v_readlane_b32 s0, v254, 40
	global_load_lds_dwordx4 v144, s[20:21]
	s_add_i32 m0, s30, 0x12000
	v_readlane_b32 s1, v254, 41
	s_add_u32 s18, s25, s0
	global_load_lds_dwordx4 v152, s[20:21]
	s_addc_u32 s19, s26, s1
	s_mov_b32 m0, s30
	s_add_i32 s31, s30, 0x2000
	global_load_lds_dwordx4 v144, s[18:19]
	s_mov_b32 m0, s31
	s_add_u32 s0, s20, 0x40000
	global_load_lds_dwordx4 v152, s[18:19]
	s_addc_u32 s1, s21, 0
	s_add_i32 m0, s30, 0x14000
	v_mov_b32_e32 v153, v145
	global_load_lds_dwordx4 v144, s[0:1]
	s_add_i32 m0, s30, 0x16000
	v_lshl_add_u64 v[6:7], s[20:21], 0, v[144:145]
	global_load_lds_dwordx4 v152, s[0:1]
	s_add_u32 s0, s18, 0x40000
	s_addc_u32 s1, s19, 0
	s_add_i32 s34, s30, 0x4000
	s_mov_b32 m0, s34
	s_add_i32 s35, s30, 0x6000
	global_load_lds_dwordx4 v144, s[0:1]
	s_mov_b32 m0, s35
	v_lshl_add_u64 v[4:5], s[20:21], 0, v[152:153]
	global_load_lds_dwordx4 v152, s[0:1]
	v_lshl_add_u64 v[2:3], s[18:19], 0, v[144:145]
	s_cmp_lg_u32 s13, 1
	v_lshl_add_u64 v[0:1], s[18:19], 0, v[152:153]
	s_cbranch_scc1 .LBB0_1028
	s_setprio 1
	s_barrier

.LBB0_1036:
	s_add_u32 s0, s18, 0xfffc0080
	s_addc_u32 s1, s19, -1
	s_add_i32 s33, 0, 0x10000
	v_add_u32_e32 v140, s33, v164
	ds_read_b128 v[124:127], v140
	ds_read_b128 v[128:131], v140 offset:1024
	ds_read_b128 v[136:139], v140 offset:2048
	ds_read_b128 v[140:143], v140 offset:3072
	s_cmp_eq_u32 s59, 12
	s_cselect_b32 s23, s13, s1
	s_cselect_b32 s22, s55, s0
	s_cselect_b32 s21, s11, s58
	s_cselect_b32 s20, s56, s57
	v_lshl_add_u64 v[162:163], s[18:19], 0, v[154:155]
	s_add_i32 m0, s30, 0xc000
	ds_read_b128 v[158:161], v166
	ds_read_b128 v[168:171], v166 offset:1024
	ds_read_b128 v[172:175], v166 offset:2048
	ds_read_b128 v[176:179], v166 offset:3072
	ds_read_b128 v[180:183], v166 offset:4096
	ds_read_b128 v[184:187], v166 offset:5120
	ds_read_b128 v[188:191], v166 offset:6144
	ds_read_b128 v[192:195], v166 offset:7168
	global_load_lds_dwordx4 v[162:163], off
	v_lshl_add_u64 v[162:163], s[18:19], 0, v[156:157]
	s_add_i32 m0, s30, 0xe000
	s_nop 0
	global_load_lds_dwordx4 v[162:163], off
	s_waitcnt lgkmcnt(8)
	s_barrier
	s_waitcnt lgkmcnt(0)

	s_waitcnt lgkmcnt(0)
	v_mfma_f32_16x16x32_bf16 v[132:135], v[124:127], v[158:161], v[132:135]
	v_mfma_f32_16x16x32_bf16 v[120:123], v[136:139], v[158:161], v[120:123]
	v_mfma_f32_16x16x32_bf16 v[108:111], v[124:127], v[172:175], v[108:111]
	v_mfma_f32_16x16x32_bf16 v[104:107], v[136:139], v[172:175], v[104:107]
	v_mfma_f32_16x16x32_bf16 v[92:95], v[124:127], v[180:183], v[92:95]
	v_mfma_f32_16x16x32_bf16 v[88:91], v[136:139], v[180:183], v[88:91]
	v_mfma_f32_16x16x32_bf16 v[76:79], v[124:127], v[188:191], v[76:79]
	v_mfma_f32_16x16x32_bf16 v[72:75], v[136:139], v[188:191], v[72:75]
	v_mfma_f32_16x16x32_bf16 v[132:135], v[128:131], v[168:171], v[132:135]
	v_mfma_f32_16x16x32_bf16 v[120:123], v[140:143], v[168:171], v[120:123]
	v_mfma_f32_16x16x32_bf16 v[108:111], v[128:131], v[176:179], v[108:111]
	v_mfma_f32_16x16x32_bf16 v[104:107], v[140:143], v[176:179], v[104:107]
	v_mfma_f32_16x16x32_bf16 v[92:95], v[128:131], v[184:187], v[92:95]
	v_mfma_f32_16x16x32_bf16 v[88:91], v[140:143], v[184:187], v[88:91]
	v_mfma_f32_16x16x32_bf16 v[76:79], v[128:131], v[192:195], v[76:79]
	v_mfma_f32_16x16x32_bf16 v[72:75], v[140:143], v[192:195], v[72:75]

	s_barrier
	s_add_i32 s38, 0, 0x14000
	v_add_u32_e32 v162, s38, v164
	s_add_i32 s0, s33, s29
	ds_read_b128 v[196:199], v162
	ds_read_b128 v[200:203], v162 offset:1024
	ds_read_b128 v[204:207], v162 offset:2048
	ds_read_b128 v[208:211], v162 offset:3072
	v_lshl_add_u64 v[162:163], s[20:21], 0, v[144:145]
	s_mov_b32 m0, s0
	v_lshl_add_u64 v[212:213], s[20:21], 0, v[152:153]
	global_load_lds_dwordx4 v[162:163], off
	s_add_i32 m0, s0, 0x2000
	s_nop 0
	global_load_lds_dwordx4 v[212:213], off
	s_barrier
	s_waitcnt lgkmcnt(0)

	s_waitcnt lgkmcnt(0)
	v_mfma_f32_16x16x32_bf16 v[116:119], v[196:199], v[158:161], v[116:119]
	v_mfma_f32_16x16x32_bf16 v[112:115], v[204:207], v[158:161], v[112:115]
	v_mfma_f32_16x16x32_bf16 v[100:103], v[196:199], v[172:175], v[100:103]
	v_mfma_f32_16x16x32_bf16 v[96:99], v[204:207], v[172:175], v[96:99]
	v_mfma_f32_16x16x32_bf16 v[84:87], v[196:199], v[180:183], v[84:87]
	v_mfma_f32_16x16x32_bf16 v[80:83], v[204:207], v[180:183], v[80:83]
	v_mfma_f32_16x16x32_bf16 v[68:71], v[196:199], v[188:191], v[68:71]
	v_mfma_f32_16x16x32_bf16 v[64:67], v[204:207], v[188:191], v[64:67]
	v_mfma_f32_16x16x32_bf16 v[116:119], v[200:203], v[168:171], v[116:119]
	v_mfma_f32_16x16x32_bf16 v[112:115], v[208:211], v[168:171], v[112:115]
	v_mfma_f32_16x16x32_bf16 v[100:103], v[200:203], v[176:179], v[100:103]
	v_mfma_f32_16x16x32_bf16 v[96:99], v[208:211], v[176:179], v[96:99]
	v_mfma_f32_16x16x32_bf16 v[84:87], v[200:203], v[184:187], v[84:87]
	v_mfma_f32_16x16x32_bf16 v[80:83], v[208:211], v[184:187], v[80:83]
	v_mfma_f32_16x16x32_bf16 v[68:71], v[200:203], v[192:195], v[68:71]
	v_mfma_f32_16x16x32_bf16 v[64:67], v[208:211], v[192:195], v[64:67]

	s_mov_b32 m0, s30
	v_lshl_add_u64 v[214:215], s[22:23], 0, v[144:145]
	s_barrier
	ds_read_b128 v[158:161], v166 offset:16384
	ds_read_b128 v[168:171], v166 offset:17408
	ds_read_b128 v[172:175], v166 offset:18432
	ds_read_b128 v[176:179], v166 offset:19456
	ds_read_b128 v[180:183], v166 offset:20480
	ds_read_b128 v[184:187], v166 offset:21504
	ds_read_b128 v[188:191], v166 offset:22528
	ds_read_b128 v[192:195], v166 offset:23552
	global_load_lds_dwordx4 v[214:215], off
	v_lshl_add_u64 v[216:217], s[22:23], 0, v[152:153]
	s_mov_b32 m0, s31
	s_nop 0
	global_load_lds_dwordx4 v[216:217], off
	s_barrier
	s_waitcnt lgkmcnt(0)

	s_waitcnt lgkmcnt(0)
	v_mfma_f32_16x16x32_bf16 v[60:63], v[124:127], v[158:161], v[60:63]
	v_mfma_f32_16x16x32_bf16 v[56:59], v[136:139], v[158:161], v[56:59]
	v_mfma_f32_16x16x32_bf16 v[44:47], v[124:127], v[172:175], v[44:47]
	v_mfma_f32_16x16x32_bf16 v[40:43], v[136:139], v[172:175], v[40:43]
	v_mfma_f32_16x16x32_bf16 v[28:31], v[124:127], v[180:183], v[28:31]
	v_mfma_f32_16x16x32_bf16 v[24:27], v[136:139], v[180:183], v[24:27]
	v_mfma_f32_16x16x32_bf16 v[12:15], v[124:127], v[188:191], v[12:15]
	v_mfma_f32_16x16x32_bf16 v[8:11], v[136:139], v[188:191], v[8:11]
	v_mfma_f32_16x16x32_bf16 v[60:63], v[128:131], v[168:171], v[60:63]
	v_mfma_f32_16x16x32_bf16 v[56:59], v[140:143], v[168:171], v[56:59]
	v_mfma_f32_16x16x32_bf16 v[44:47], v[128:131], v[176:179], v[44:47]
	v_mfma_f32_16x16x32_bf16 v[40:43], v[140:143], v[176:179], v[40:43]
	v_mfma_f32_16x16x32_bf16 v[28:31], v[128:131], v[184:187], v[28:31]
	v_mfma_f32_16x16x32_bf16 v[24:27], v[140:143], v[184:187], v[24:27]
	v_mfma_f32_16x16x32_bf16 v[12:15], v[128:131], v[192:195], v[12:15]
	v_mfma_f32_16x16x32_bf16 v[8:11], v[140:143], v[192:195], v[8:11]

	s_barrier
	s_add_u32 s0, s20, 0x40000
	s_addc_u32 s1, s21, 0
	s_add_i32 s33, s38, s29
	v_lshl_add_u64 v[124:125], s[0:1], 0, v[144:145]
	s_mov_b32 m0, s33
	s_nop 0
	global_load_lds_dwordx4 v[124:125], off
	v_lshl_add_u64 v[124:125], s[0:1], 0, v[152:153]
	s_add_i32 m0, s33, 0x2000
	s_nop 0
	global_load_lds_dwordx4 v[124:125], off
	s_waitcnt vmcnt(6)
	s_barrier

	v_mfma_f32_16x16x32_bf16 v[52:55], v[196:199], v[158:161], v[52:55]
	v_mfma_f32_16x16x32_bf16 v[48:51], v[204:207], v[158:161], v[48:51]
	v_mfma_f32_16x16x32_bf16 v[36:39], v[196:199], v[172:175], v[36:39]
	v_mfma_f32_16x16x32_bf16 v[32:35], v[204:207], v[172:175], v[32:35]
	v_mfma_f32_16x16x32_bf16 v[20:23], v[196:199], v[180:183], v[20:23]
	v_mfma_f32_16x16x32_bf16 v[16:19], v[204:207], v[180:183], v[16:19]
	v_mfma_f32_16x16x32_bf16 v[4:7], v[196:199], v[188:191], v[4:7]
	v_mfma_f32_16x16x32_bf16 v[0:3], v[204:207], v[188:191], v[0:3]
	v_mfma_f32_16x16x32_bf16 v[52:55], v[200:203], v[168:171], v[52:55]
	v_mfma_f32_16x16x32_bf16 v[48:51], v[208:211], v[168:171], v[48:51]
	v_mfma_f32_16x16x32_bf16 v[36:39], v[200:203], v[176:179], v[36:39]
	v_mfma_f32_16x16x32_bf16 v[32:35], v[208:211], v[176:179], v[32:35]
	v_mfma_f32_16x16x32_bf16 v[20:23], v[200:203], v[184:187], v[20:23]
	v_mfma_f32_16x16x32_bf16 v[16:19], v[208:211], v[184:187], v[16:19]
	v_mfma_f32_16x16x32_bf16 v[4:7], v[200:203], v[192:195], v[4:7]
	v_mfma_f32_16x16x32_bf16 v[0:3], v[208:211], v[192:195], v[0:3]

	s_add_i32 s33, 0, 0x18000
	v_add_u32_e32 v140, s33, v164
	s_barrier
	ds_read_b128 v[124:127], v140
	ds_read_b128 v[128:131], v140 offset:1024
	ds_read_b128 v[136:139], v140 offset:2048
	ds_read_b128 v[140:143], v140 offset:3072
	s_add_u32 s0, s22, 0x40000
	s_addc_u32 s1, s23, 0
	s_mov_b32 m0, s34
	v_lshl_add_u64 v[196:197], s[0:1], 0, v[144:145]
	ds_read_b128 v[158:161], v166 offset:32768
	ds_read_b128 v[168:171], v166 offset:33792
	ds_read_b128 v[172:175], v166 offset:34816
	ds_read_b128 v[176:179], v166 offset:35840
	ds_read_b128 v[180:183], v166 offset:36864
	ds_read_b128 v[184:187], v166 offset:37888
	ds_read_b128 v[188:191], v166 offset:38912
	ds_read_b128 v[192:195], v166 offset:39936
	global_load_lds_dwordx4 v[196:197], off
	v_lshl_add_u64 v[196:197], s[0:1], 0, v[152:153]
	s_mov_b32 m0, s35
	s_nop 0
	global_load_lds_dwordx4 v[196:197], off
	s_waitcnt lgkmcnt(8)
	s_barrier
	s_waitcnt lgkmcnt(0)

	s_waitcnt lgkmcnt(0)
	v_mfma_f32_16x16x32_bf16 v[132:135], v[124:127], v[158:161], v[132:135]
	v_mfma_f32_16x16x32_bf16 v[120:123], v[136:139], v[158:161], v[120:123]
	v_mfma_f32_16x16x32_bf16 v[108:111], v[124:127], v[172:175], v[108:111]
	v_mfma_f32_16x16x32_bf16 v[104:107], v[136:139], v[172:175], v[104:107]
	v_mfma_f32_16x16x32_bf16 v[92:95], v[124:127], v[180:183], v[92:95]
	v_mfma_f32_16x16x32_bf16 v[88:91], v[136:139], v[180:183], v[88:91]
	v_mfma_f32_16x16x32_bf16 v[76:79], v[124:127], v[188:191], v[76:79]
	v_mfma_f32_16x16x32_bf16 v[72:75], v[136:139], v[188:191], v[72:75]
	v_mfma_f32_16x16x32_bf16 v[132:135], v[128:131], v[168:171], v[132:135]
	v_mfma_f32_16x16x32_bf16 v[120:123], v[140:143], v[168:171], v[120:123]
	v_mfma_f32_16x16x32_bf16 v[108:111], v[128:131], v[176:179], v[108:111]
	v_mfma_f32_16x16x32_bf16 v[104:107], v[140:143], v[176:179], v[104:107]
	v_mfma_f32_16x16x32_bf16 v[92:95], v[128:131], v[184:187], v[92:95]
	v_mfma_f32_16x16x32_bf16 v[88:91], v[140:143], v[184:187], v[88:91]
	v_mfma_f32_16x16x32_bf16 v[76:79], v[128:131], v[192:195], v[76:79]
	v_mfma_f32_16x16x32_bf16 v[72:75], v[140:143], v[192:195], v[72:75]

	s_barrier
	s_add_i32 s22, 0, 0x1c000
	s_add_i32 s0, s33, s29
	v_add_u32_e32 v167, s22, v164
	v_lshl_add_u64 v[162:163], v[162:163], 0, s[86:87]
	s_mov_b32 m0, s0
	ds_read_b128 v[196:199], v167
	ds_read_b128 v[200:203], v167 offset:1024
	ds_read_b128 v[204:207], v167 offset:2048
	ds_read_b128 v[208:211], v167 offset:3072
	global_load_lds_dwordx4 v[162:163], off
	v_lshl_add_u64 v[162:163], v[212:213], 0, s[86:87]
	s_add_i32 m0, s0, 0x2000
	s_nop 0
	global_load_lds_dwordx4 v[162:163], off
	s_barrier
	s_waitcnt lgkmcnt(0)

	s_waitcnt lgkmcnt(0)
	v_mfma_f32_16x16x32_bf16 v[116:119], v[196:199], v[158:161], v[116:119]
	v_mfma_f32_16x16x32_bf16 v[112:115], v[204:207], v[158:161], v[112:115]
	v_mfma_f32_16x16x32_bf16 v[100:103], v[196:199], v[172:175], v[100:103]
	v_mfma_f32_16x16x32_bf16 v[96:99], v[204:207], v[172:175], v[96:99]
	v_mfma_f32_16x16x32_bf16 v[84:87], v[196:199], v[180:183], v[84:87]
	v_mfma_f32_16x16x32_bf16 v[80:83], v[204:207], v[180:183], v[80:83]
	v_mfma_f32_16x16x32_bf16 v[68:71], v[196:199], v[188:191], v[68:71]
	v_mfma_f32_16x16x32_bf16 v[64:67], v[204:207], v[188:191], v[64:67]
	v_mfma_f32_16x16x32_bf16 v[116:119], v[200:203], v[168:171], v[116:119]
	v_mfma_f32_16x16x32_bf16 v[112:115], v[208:211], v[168:171], v[112:115]
	v_mfma_f32_16x16x32_bf16 v[100:103], v[200:203], v[176:179], v[100:103]
	v_mfma_f32_16x16x32_bf16 v[96:99], v[208:211], v[176:179], v[96:99]
	v_mfma_f32_16x16x32_bf16 v[84:87], v[200:203], v[184:187], v[84:87]
	v_mfma_f32_16x16x32_bf16 v[80:83], v[208:211], v[184:187], v[80:83]
	v_mfma_f32_16x16x32_bf16 v[68:71], v[200:203], v[192:195], v[68:71]
	v_mfma_f32_16x16x32_bf16 v[64:67], v[208:211], v[192:195], v[64:67]

	s_mov_b32 m0, s44
	v_lshl_add_u64 v[162:163], v[214:215], 0, s[86:87]
	s_barrier
	ds_read_b128 v[158:161], v166 offset:49152
	ds_read_b128 v[168:171], v166 offset:50176
	ds_read_b128 v[172:175], v166 offset:51200
	ds_read_b128 v[176:179], v166 offset:52224
	ds_read_b128 v[180:183], v166 offset:53248
	ds_read_b128 v[184:187], v166 offset:54272
	ds_read_b128 v[188:191], v166 offset:55296
	ds_read_b128 v[192:195], v166 offset:56320
	global_load_lds_dwordx4 v[162:163], off
	v_lshl_add_u64 v[162:163], v[216:217], 0, s[86:87]
	s_mov_b32 m0, s45
	s_nop 0
	global_load_lds_dwordx4 v[162:163], off
	s_barrier
	s_waitcnt lgkmcnt(0)

	s_waitcnt lgkmcnt(0)
	v_mfma_f32_16x16x32_bf16 v[60:63], v[124:127], v[158:161], v[60:63]
	v_mfma_f32_16x16x32_bf16 v[56:59], v[136:139], v[158:161], v[56:59]
	v_mfma_f32_16x16x32_bf16 v[44:47], v[124:127], v[172:175], v[44:47]
	v_mfma_f32_16x16x32_bf16 v[40:43], v[136:139], v[172:175], v[40:43]
	v_mfma_f32_16x16x32_bf16 v[28:31], v[124:127], v[180:183], v[28:31]
	v_mfma_f32_16x16x32_bf16 v[24:27], v[136:139], v[180:183], v[24:27]
	v_mfma_f32_16x16x32_bf16 v[12:15], v[124:127], v[188:191], v[12:15]
	v_mfma_f32_16x16x32_bf16 v[8:11], v[136:139], v[188:191], v[8:11]
	v_mfma_f32_16x16x32_bf16 v[60:63], v[128:131], v[168:171], v[60:63]
	v_mfma_f32_16x16x32_bf16 v[56:59], v[140:143], v[168:171], v[56:59]
	v_mfma_f32_16x16x32_bf16 v[44:47], v[128:131], v[176:179], v[44:47]
	v_mfma_f32_16x16x32_bf16 v[40:43], v[140:143], v[176:179], v[40:43]
	v_mfma_f32_16x16x32_bf16 v[28:31], v[128:131], v[184:187], v[28:31]
	v_mfma_f32_16x16x32_bf16 v[24:27], v[140:143], v[184:187], v[24:27]
	v_mfma_f32_16x16x32_bf16 v[12:15], v[128:131], v[192:195], v[12:15]
	v_mfma_f32_16x16x32_bf16 v[8:11], v[140:143], v[192:195], v[8:11]

	s_barrier
	s_add_u32 s0, s20, 0x40080
	s_addc_u32 s1, s21, 0
	s_add_i32 s20, s22, s29
	v_lshl_add_u64 v[124:125], s[0:1], 0, v[144:145]
	s_mov_b32 m0, s20
	s_nop 0
	global_load_lds_dwordx4 v[124:125], off
	v_lshl_add_u64 v[124:125], s[0:1], 0, v[152:153]
	s_add_i32 m0, s20, 0x2000
	s_nop 0
	global_load_lds_dwordx4 v[124:125], off
	s_waitcnt vmcnt(6)
	s_barrier

	v_mfma_f32_16x16x32_bf16 v[52:55], v[196:199], v[158:161], v[52:55]
	v_mfma_f32_16x16x32_bf16 v[48:51], v[204:207], v[158:161], v[48:51]
	v_mfma_f32_16x16x32_bf16 v[36:39], v[196:199], v[172:175], v[36:39]
	v_mfma_f32_16x16x32_bf16 v[32:35], v[204:207], v[172:175], v[32:35]
	v_mfma_f32_16x16x32_bf16 v[20:23], v[196:199], v[180:183], v[20:23]
	v_mfma_f32_16x16x32_bf16 v[16:19], v[204:207], v[180:183], v[16:19]
	v_mfma_f32_16x16x32_bf16 v[4:7], v[196:199], v[188:191], v[4:7]
	v_mfma_f32_16x16x32_bf16 v[0:3], v[204:207], v[188:191], v[0:3]
	v_mfma_f32_16x16x32_bf16 v[52:55], v[200:203], v[168:171], v[52:55]
	v_mfma_f32_16x16x32_bf16 v[48:51], v[208:211], v[168:171], v[48:51]
	v_mfma_f32_16x16x32_bf16 v[36:39], v[200:203], v[176:179], v[36:39]
	v_mfma_f32_16x16x32_bf16 v[32:35], v[208:211], v[176:179], v[32:35]
	v_mfma_f32_16x16x32_bf16 v[20:23], v[200:203], v[184:187], v[20:23]
	v_mfma_f32_16x16x32_bf16 v[16:19], v[208:211], v[184:187], v[16:19]
	v_mfma_f32_16x16x32_bf16 v[4:7], v[200:203], v[192:195], v[4:7]
	v_mfma_f32_16x16x32_bf16 v[0:3], v[208:211], v[192:195], v[0:3]

	s_add_i32 s59, s59, 2
	s_add_u32 s18, s18, 0x100
	s_addc_u32 s19, s19, 0
	s_add_u32 s57, s57, 0x100
	s_addc_u32 s58, s58, 0
	s_cmp_gt_u32 s59, 13
	s_barrier
	s_cbranch_scc0 .LBB0_1036
	s_ashr_i32 s0, s49, 4
	s_mul_i32 s0, s0, 3
	v_lshl_add_u32 v162, s49, 8, v146
	v_lshl_or_b32 v160, s54, 8, v165
	s_ashr_i32 s1, s0, 31
	v_ashrrev_i32_e32 v163, 31, v162
	s_lshl_b64 s[0:1], s[0:1], 12
	v_ashrrev_i32_e32 v161, 31, v160
	v_lshlrev_b64 v[158:159], 10, v[162:163]
	s_add_u32 s0, s36, s0
	v_lshl_add_u64 v[158:159], v[158:159], 0, v[160:161]
	s_addc_u32 s1, s37, s1
	v_lshlrev_b64 v[158:159], 2, v[158:159]
	v_lshl_add_u64 v[124:125], v[160:161], 2, s[0:1]
	v_lshl_add_u64 v[172:173], s[6:7], 0, v[158:159]
	global_load_dwordx4 v[140:143], v[124:125], off
	global_load_dwordx4 v[136:139], v[124:125], off offset:64
	global_load_dwordx4 v[128:131], v[124:125], off offset:512
	s_nop 0
	global_load_dwordx4 v[124:127], v[124:125], off offset:576
	s_mov_b64 s[0:1], 0x80000
	s_and_b64 vcc, exec, s[4:5]
	s_mov_b32 s54, s10
	s_mov_b32 s49, s12
	s_mov_b64 s[20:21], s[16:17]
	s_mov_b64 s[18:19], s[14:15]
	v_lshl_add_u64 v[210:211], s[6:7], 0, v[158:159]
	global_load_dwordx4 v[174:177], v[210:211], off
	global_load_dwordx4 v[178:181], v[210:211], off offset:64
	global_load_dwordx4 v[182:185], v[210:211], off offset:512
	global_load_dwordx4 v[186:189], v[210:211], off offset:576
	s_mov_b64 s[0:1], 0x10000
	v_lshl_add_u64 v[210:211], v[158:159], 0, s[0:1]
	v_lshl_add_u64 v[210:211], s[6:7], 0, v[210:211]
	global_load_dwordx4 v[190:193], v[210:211], off
	global_load_dwordx4 v[194:197], v[210:211], off offset:64
	global_load_dwordx4 v[198:201], v[210:211], off offset:512
	global_load_dwordx4 v[202:205], v[210:211], off offset:576
	v_lshl_add_u64 v[168:169], s[8:9], 0, v[158:159]
	s_waitcnt vmcnt(7)
	v_pk_fma_f32 v[134:135], v[134:135], v[142:143], v[176:177]
	v_pk_fma_f32 v[132:133], v[132:133], v[140:141], v[174:175]
	global_store_dwordx4 v[168:169], v[132:135], off
	s_waitcnt vmcnt(7)
	v_pk_fma_f32 v[122:123], v[122:123], v[138:139], v[180:181]
	v_pk_fma_f32 v[120:121], v[120:121], v[136:137], v[178:179]
	global_store_dwordx4 v[168:169], v[120:123], off offset:64
	s_waitcnt vmcnt(7)
	v_pk_fma_f32 v[118:119], v[118:119], v[130:131], v[184:185]
	v_pk_fma_f32 v[116:117], v[116:117], v[128:129], v[182:183]
	global_store_dwordx4 v[168:169], v[116:119], off offset:512
	s_waitcnt vmcnt(7)
	v_pk_fma_f32 v[114:115], v[114:115], v[126:127], v[188:189]
	v_pk_fma_f32 v[112:113], v[112:113], v[124:125], v[186:187]
	global_store_dwordx4 v[168:169], v[112:115], off offset:576
	s_mov_b64 s[0:1], 0x10000
	v_lshl_add_u64 v[168:169], v[158:159], 0, s[0:1]
	v_lshl_add_u64 v[168:169], s[8:9], 0, v[168:169]
	s_waitcnt vmcnt(7)
	v_pk_fma_f32 v[110:111], v[110:111], v[142:143], v[192:193]
	v_pk_fma_f32 v[108:109], v[108:109], v[140:141], v[190:191]
	global_store_dwordx4 v[168:169], v[108:111], off
	s_waitcnt vmcnt(7)
	v_pk_fma_f32 v[106:107], v[106:107], v[138:139], v[196:197]
	v_pk_fma_f32 v[104:105], v[104:105], v[136:137], v[194:195]
	global_store_dwordx4 v[168:169], v[104:107], off offset:64
	s_waitcnt vmcnt(7)
	v_pk_fma_f32 v[102:103], v[102:103], v[130:131], v[200:201]
	v_pk_fma_f32 v[100:101], v[100:101], v[128:129], v[198:199]
	global_store_dwordx4 v[168:169], v[100:103], off offset:512
	s_waitcnt vmcnt(7)
	v_pk_fma_f32 v[98:99], v[98:99], v[126:127], v[204:205]
	v_pk_fma_f32 v[96:97], v[96:97], v[124:125], v[202:203]
	global_store_dwordx4 v[168:169], v[96:99], off offset:576
	s_mov_b64 s[0:1], 0x20000
	v_lshl_add_u64 v[210:211], v[158:159], 0, s[0:1]
	v_lshl_add_u64 v[210:211], s[6:7], 0, v[210:211]
	global_load_dwordx4 v[174:177], v[210:211], off
	global_load_dwordx4 v[178:181], v[210:211], off offset:64
	global_load_dwordx4 v[182:185], v[210:211], off offset:512
	global_load_dwordx4 v[186:189], v[210:211], off offset:576
	s_mov_b64 s[0:1], 0x30000
	v_lshl_add_u64 v[210:211], v[158:159], 0, s[0:1]
	v_lshl_add_u64 v[210:211], s[6:7], 0, v[210:211]
	global_load_dwordx4 v[190:193], v[210:211], off
	global_load_dwordx4 v[194:197], v[210:211], off offset:64
	global_load_dwordx4 v[198:201], v[210:211], off offset:512
	global_load_dwordx4 v[202:205], v[210:211], off offset:576
	s_mov_b64 s[0:1], 0x20000
	v_lshl_add_u64 v[168:169], v[158:159], 0, s[0:1]
	v_lshl_add_u64 v[168:169], s[8:9], 0, v[168:169]
	s_waitcnt vmcnt(7)
	v_pk_fma_f32 v[94:95], v[94:95], v[142:143], v[176:177]
	v_pk_fma_f32 v[92:93], v[92:93], v[140:141], v[174:175]
	global_store_dwordx4 v[168:169], v[92:95], off
	s_waitcnt vmcnt(7)
	v_pk_fma_f32 v[90:91], v[90:91], v[138:139], v[180:181]
	v_pk_fma_f32 v[88:89], v[88:89], v[136:137], v[178:179]
	global_store_dwordx4 v[168:169], v[88:91], off offset:64
	s_waitcnt vmcnt(7)
	v_pk_fma_f32 v[86:87], v[86:87], v[130:131], v[184:185]
	v_pk_fma_f32 v[84:85], v[84:85], v[128:129], v[182:183]
	global_store_dwordx4 v[168:169], v[84:87], off offset:512
	s_waitcnt vmcnt(7)
	v_pk_fma_f32 v[82:83], v[82:83], v[126:127], v[188:189]
	v_pk_fma_f32 v[80:81], v[80:81], v[124:125], v[186:187]
	global_store_dwordx4 v[168:169], v[80:83], off offset:576
	s_mov_b64 s[0:1], 0x30000
	v_lshl_add_u64 v[168:169], v[158:159], 0, s[0:1]
	v_lshl_add_u64 v[168:169], s[8:9], 0, v[168:169]
	s_waitcnt vmcnt(7)
	v_pk_fma_f32 v[78:79], v[78:79], v[142:143], v[192:193]
	v_pk_fma_f32 v[76:77], v[76:77], v[140:141], v[190:191]
	global_store_dwordx4 v[168:169], v[76:79], off
	s_waitcnt vmcnt(7)
	v_pk_fma_f32 v[74:75], v[74:75], v[138:139], v[196:197]
	v_pk_fma_f32 v[72:73], v[72:73], v[136:137], v[194:195]
	global_store_dwordx4 v[168:169], v[72:75], off offset:64
	s_waitcnt vmcnt(7)
	v_pk_fma_f32 v[70:71], v[70:71], v[130:131], v[200:201]
	v_pk_fma_f32 v[68:69], v[68:69], v[128:129], v[198:199]
	global_store_dwordx4 v[168:169], v[68:71], off offset:512
	s_waitcnt vmcnt(7)
	v_pk_fma_f32 v[66:67], v[66:67], v[126:127], v[204:205]
	v_pk_fma_f32 v[64:65], v[64:65], v[124:125], v[202:203]
	global_store_dwordx4 v[168:169], v[64:67], off offset:576
	s_mov_b64 s[0:1], 0x80000
	v_lshl_add_u64 v[210:211], v[158:159], 0, s[0:1]
	v_lshl_add_u64 v[210:211], s[6:7], 0, v[210:211]
	global_load_dwordx4 v[174:177], v[210:211], off
	global_load_dwordx4 v[178:181], v[210:211], off offset:64
	global_load_dwordx4 v[182:185], v[210:211], off offset:512
	global_load_dwordx4 v[186:189], v[210:211], off offset:576
	s_mov_b64 s[0:1], 0x90000
	v_lshl_add_u64 v[210:211], v[158:159], 0, s[0:1]
	v_lshl_add_u64 v[210:211], s[6:7], 0, v[210:211]
	global_load_dwordx4 v[190:193], v[210:211], off
	global_load_dwordx4 v[194:197], v[210:211], off offset:64
	global_load_dwordx4 v[198:201], v[210:211], off offset:512
	global_load_dwordx4 v[202:205], v[210:211], off offset:576
	s_mov_b64 s[0:1], 0x80000
	v_lshl_add_u64 v[168:169], v[158:159], 0, s[0:1]
	v_lshl_add_u64 v[168:169], s[8:9], 0, v[168:169]
	s_waitcnt vmcnt(7)
	v_pk_fma_f32 v[62:63], v[62:63], v[142:143], v[176:177]
	v_pk_fma_f32 v[60:61], v[60:61], v[140:141], v[174:175]
	global_store_dwordx4 v[168:169], v[60:63], off
	s_waitcnt vmcnt(7)
	v_pk_fma_f32 v[58:59], v[58:59], v[138:139], v[180:181]
	v_pk_fma_f32 v[56:57], v[56:57], v[136:137], v[178:179]
	global_store_dwordx4 v[168:169], v[56:59], off offset:64
	s_waitcnt vmcnt(7)
	v_pk_fma_f32 v[54:55], v[54:55], v[130:131], v[184:185]
	v_pk_fma_f32 v[52:53], v[52:53], v[128:129], v[182:183]
	global_store_dwordx4 v[168:169], v[52:55], off offset:512
	s_waitcnt vmcnt(7)
	v_pk_fma_f32 v[50:51], v[50:51], v[126:127], v[188:189]
	v_pk_fma_f32 v[48:49], v[48:49], v[124:125], v[186:187]
	global_store_dwordx4 v[168:169], v[48:51], off offset:576
	s_mov_b64 s[0:1], 0x90000
	v_lshl_add_u64 v[168:169], v[158:159], 0, s[0:1]
	v_lshl_add_u64 v[168:169], s[8:9], 0, v[168:169]
	s_waitcnt vmcnt(7)
	v_pk_fma_f32 v[46:47], v[46:47], v[142:143], v[192:193]
	v_pk_fma_f32 v[44:45], v[44:45], v[140:141], v[190:191]
	global_store_dwordx4 v[168:169], v[44:47], off
	s_waitcnt vmcnt(7)
	v_pk_fma_f32 v[42:43], v[42:43], v[138:139], v[196:197]
	v_pk_fma_f32 v[40:41], v[40:41], v[136:137], v[194:195]
	global_store_dwordx4 v[168:169], v[40:43], off offset:64
	s_waitcnt vmcnt(7)
	v_pk_fma_f32 v[38:39], v[38:39], v[130:131], v[200:201]
	v_pk_fma_f32 v[36:37], v[36:37], v[128:129], v[198:199]
	global_store_dwordx4 v[168:169], v[36:39], off offset:512
	s_waitcnt vmcnt(7)
	v_pk_fma_f32 v[34:35], v[34:35], v[126:127], v[204:205]
	v_pk_fma_f32 v[32:33], v[32:33], v[124:125], v[202:203]
	global_store_dwordx4 v[168:169], v[32:35], off offset:576
	s_mov_b64 s[0:1], 0xa0000
	v_lshl_add_u64 v[210:211], v[158:159], 0, s[0:1]
	v_lshl_add_u64 v[210:211], s[6:7], 0, v[210:211]
	global_load_dwordx4 v[174:177], v[210:211], off
	global_load_dwordx4 v[178:181], v[210:211], off offset:64
	global_load_dwordx4 v[182:185], v[210:211], off offset:512
	global_load_dwordx4 v[186:189], v[210:211], off offset:576
	s_mov_b64 s[0:1], 0xb0000
	v_lshl_add_u64 v[210:211], v[158:159], 0, s[0:1]
	v_lshl_add_u64 v[210:211], s[6:7], 0, v[210:211]
	global_load_dwordx4 v[190:193], v[210:211], off
	global_load_dwordx4 v[194:197], v[210:211], off offset:64
	global_load_dwordx4 v[198:201], v[210:211], off offset:512
	global_load_dwordx4 v[202:205], v[210:211], off offset:576
	s_mov_b64 s[0:1], 0xa0000
	v_lshl_add_u64 v[168:169], v[158:159], 0, s[0:1]
	v_lshl_add_u64 v[168:169], s[8:9], 0, v[168:169]
	s_waitcnt vmcnt(7)
	v_pk_fma_f32 v[30:31], v[30:31], v[142:143], v[176:177]
	v_pk_fma_f32 v[28:29], v[28:29], v[140:141], v[174:175]
	global_store_dwordx4 v[168:169], v[28:31], off
	s_waitcnt vmcnt(7)
	v_pk_fma_f32 v[26:27], v[26:27], v[138:139], v[180:181]
	v_pk_fma_f32 v[24:25], v[24:25], v[136:137], v[178:179]
	global_store_dwordx4 v[168:169], v[24:27], off offset:64
	s_waitcnt vmcnt(7)
	v_pk_fma_f32 v[22:23], v[22:23], v[130:131], v[184:185]
	v_pk_fma_f32 v[20:21], v[20:21], v[128:129], v[182:183]
	global_store_dwordx4 v[168:169], v[20:23], off offset:512
	s_waitcnt vmcnt(7)
	v_pk_fma_f32 v[18:19], v[18:19], v[126:127], v[188:189]
	v_pk_fma_f32 v[16:17], v[16:17], v[124:125], v[186:187]
	global_store_dwordx4 v[168:169], v[16:19], off offset:576
	s_mov_b64 s[0:1], 0xb0000
	v_lshl_add_u64 v[168:169], v[158:159], 0, s[0:1]
	v_lshl_add_u64 v[168:169], s[8:9], 0, v[168:169]
	s_waitcnt vmcnt(7)
	v_pk_fma_f32 v[14:15], v[14:15], v[142:143], v[192:193]
	v_pk_fma_f32 v[12:13], v[12:13], v[140:141], v[190:191]
	global_store_dwordx4 v[168:169], v[12:15], off
	s_waitcnt vmcnt(7)
	v_pk_fma_f32 v[10:11], v[10:11], v[138:139], v[196:197]
	v_pk_fma_f32 v[8:9], v[8:9], v[136:137], v[194:195]
	global_store_dwordx4 v[168:169], v[8:11], off offset:64
	s_waitcnt vmcnt(7)
	v_pk_fma_f32 v[6:7], v[6:7], v[130:131], v[200:201]
	v_pk_fma_f32 v[4:5], v[4:5], v[128:129], v[198:199]
	global_store_dwordx4 v[168:169], v[4:7], off offset:512
	s_waitcnt vmcnt(7)
	v_pk_fma_f32 v[2:3], v[2:3], v[126:127], v[204:205]
	v_pk_fma_f32 v[0:1], v[0:1], v[124:125], v[202:203]
	global_store_dwordx4 v[168:169], v[0:3], off offset:576
	s_cbranch_vccz .LBB0_1029
	s_waitcnt vmcnt(0)
	s_cmpk_gt_u32 s24, 0xff
	s_cbranch_scc1 .LBB0_1040
	s_barrier
